# strategy 7 instruction selection: SEL softmax uses v_pk_fma_f32/v_pk_add_f32 (row-sum order changes, still f32)
# baseline (speedup 1.0000x reference)
; #define MFMA32(a, b, c) __builtin_amdgcn_mfma_f32_32x32x16_bf16((a), (b), (c), 0, 0, 0)
; template <int DQK, int MODE> ...
;     ...
;             float ls = 0.f;
; #pragma unroll
;             for (int kb = 0; kb < 2; ++kb)
; #pragma unroll
;                 for (int i = 0; i < 16; ++i) { const float p = __builtin_amdgcn_exp2f(__builtin_fmaf(s[kb][i], sc, -mref)); s[kb][i] = p; ls += p; }
;             l += ls;
;             {
;                 asm volatile("s_waitcnt lgkmcnt(0)" ::: "memory");
; #pragma unroll
;                 for (int kb = 0; kb < 2; ++kb)
; #pragma unroll
;                     for (int s2 = 0; s2 < 2; ++s2)
; #pragma unroll
;                         for (int d0 = 0; d0 < 2; ++d0) { asm volatile("" : "+v"(vlo[kb][s2][d0]), "+v"(vhi[kb][s2][d0])); }
;                 __builtin_amdgcn_s_setprio(1);
; #pragma unroll
;                 for (int kb = 0; kb < 2; ++kb)
; #pragma unroll
;                     for (int s2 = 0; s2 < 2; ++s2) {
;                         const bf16x8 pf = pack8(s[kb], s2);
; #pragma unroll
;                         for (int d0 = 0; d0 < 2; ++d0) {
;                             const s16x4 lo = vlo[kb][s2][d0], hh = vhi[kb][s2][d0];
;                             const bf16x8 vfr = (bf16x8){lo[0], lo[1], lo[2], lo[3], hh[0], hh[1], hh[2], hh[3]};
;                             o[d0] = MFMA32(vfr, pf, o[d0]);
;                         }
;                     }
;                 __builtin_amdgcn_s_setprio(0);
;             }
.LBB0_1318:
	v_xor_b32_e32 v202, 0x80000000, v14
	v_cndmask_b32_e64 v202, v204, v202, s[6:7]
	v_pk_fma_f32 v[64:65], v[64:65], s[78:79], v[202:203] op_sel_hi:[1,0,0]
	v_pk_fma_f32 v[66:67], v[66:67], s[78:79], v[202:203] op_sel_hi:[1,0,0]
	v_pk_fma_f32 v[68:69], v[68:69], s[78:79], v[202:203] op_sel_hi:[1,0,0]
	v_pk_fma_f32 v[70:71], v[70:71], s[78:79], v[202:203] op_sel_hi:[1,0,0]
	v_pk_fma_f32 v[72:73], v[72:73], s[78:79], v[202:203] op_sel_hi:[1,0,0]
	v_pk_fma_f32 v[74:75], v[74:75], s[78:79], v[202:203] op_sel_hi:[1,0,0]
	v_pk_fma_f32 v[76:77], v[76:77], s[78:79], v[202:203] op_sel_hi:[1,0,0]
	v_pk_fma_f32 v[78:79], v[78:79], s[78:79], v[202:203] op_sel_hi:[1,0,0]
	v_pk_fma_f32 v[48:49], v[48:49], s[78:79], v[202:203] op_sel_hi:[1,0,0]
	v_pk_fma_f32 v[50:51], v[50:51], s[78:79], v[202:203] op_sel_hi:[1,0,0]
	v_pk_fma_f32 v[52:53], v[52:53], s[78:79], v[202:203] op_sel_hi:[1,0,0]
	v_pk_fma_f32 v[54:55], v[54:55], s[78:79], v[202:203] op_sel_hi:[1,0,0]
	v_pk_fma_f32 v[56:57], v[56:57], s[78:79], v[202:203] op_sel_hi:[1,0,0]
	v_pk_fma_f32 v[58:59], v[58:59], s[78:79], v[202:203] op_sel_hi:[1,0,0]
	v_pk_fma_f32 v[60:61], v[60:61], s[78:79], v[202:203] op_sel_hi:[1,0,0]
	v_pk_fma_f32 v[62:63], v[62:63], s[78:79], v[202:203] op_sel_hi:[1,0,0]
	v_exp_f32_e32 v64, v64
	v_exp_f32_e32 v65, v65
	v_exp_f32_e32 v66, v66
	v_exp_f32_e32 v67, v67
	v_exp_f32_e32 v68, v68
	v_exp_f32_e32 v69, v69
	v_exp_f32_e32 v70, v70
	v_exp_f32_e32 v71, v71
	v_exp_f32_e32 v72, v72
	v_exp_f32_e32 v73, v73
	v_exp_f32_e32 v74, v74
	v_exp_f32_e32 v75, v75
	v_exp_f32_e32 v76, v76
	v_exp_f32_e32 v77, v77
	v_exp_f32_e32 v78, v78
	v_exp_f32_e32 v79, v79
	v_exp_f32_e32 v133, v48
	v_exp_f32_e32 v134, v49
	v_exp_f32_e32 v135, v50
	v_exp_f32_e32 v136, v51
	v_exp_f32_e32 v52, v52
	v_exp_f32_e32 v53, v53
	v_exp_f32_e32 v54, v54
	v_exp_f32_e32 v55, v55
	v_exp_f32_e32 v56, v56
	v_exp_f32_e32 v57, v57
	v_exp_f32_e32 v58, v58
	v_exp_f32_e32 v59, v59
	v_exp_f32_e32 v60, v60
	v_exp_f32_e32 v61, v61
	v_exp_f32_e32 v62, v62
	v_exp_f32_e32 v63, v63
	v_pk_add_f32 v[232:233], v[64:65], v[66:67]
	v_pk_add_f32 v[232:233], v[232:233], v[68:69]
	v_pk_add_f32 v[232:233], v[232:233], v[70:71]
	v_pk_add_f32 v[232:233], v[232:233], v[72:73]
	v_pk_add_f32 v[232:233], v[232:233], v[74:75]
	v_pk_add_f32 v[232:233], v[232:233], v[76:77]
	v_pk_add_f32 v[232:233], v[232:233], v[78:79]
	v_pk_add_f32 v[232:233], v[232:233], v[134:135]
	v_pk_add_f32 v[232:233], v[232:233], v[52:53]
	v_pk_add_f32 v[232:233], v[232:233], v[54:55]
	v_pk_add_f32 v[232:233], v[232:233], v[56:57]
	v_pk_add_f32 v[232:233], v[232:233], v[58:59]
	v_pk_add_f32 v[232:233], v[232:233], v[60:61]
	v_pk_add_f32 v[232:233], v[232:233], v[62:63]
	s_waitcnt lgkmcnt(0)
	v_add_f32_e32 v132, v133, v136
	v_add_f32_e32 v232, v232, v233
	v_add_f32_e32 v132, v132, v232
	s_setprio 1
	v_cvt_pk_bf16_f32 v48, v64, v65
	v_cvt_pk_bf16_f32 v49, v66, v67
	v_cvt_pk_bf16_f32 v50, v68, v69
	v_cvt_pk_bf16_f32 v51, v70, v71
	v_add_f32_e32 v179, v179, v132
	s_nop 0
	v_mfma_f32_32x32x16_bf16 v[32:47], v[116:119], v[48:51], v[32:47]
	v_mfma_f32_32x32x16_bf16 v[16:31], v[112:115], v[48:51], v[16:31]
	v_cvt_pk_bf16_f32 v48, v72, v73
	v_cvt_pk_bf16_f32 v49, v74, v75
	v_cvt_pk_bf16_f32 v50, v76, v77
	v_cvt_pk_bf16_f32 v51, v78, v79
	s_nop 1
	v_mfma_f32_32x32x16_bf16 v[32:47], v[100:103], v[48:51], v[32:47]
	v_mfma_f32_32x32x16_bf16 v[16:31], v[96:99], v[48:51], v[16:31]
	v_cvt_pk_bf16_f32 v48, v133, v134
	v_cvt_pk_bf16_f32 v49, v135, v136
	v_cvt_pk_bf16_f32 v50, v52, v53
	v_cvt_pk_bf16_f32 v51, v54, v55
	s_nop 1
	v_mfma_f32_32x32x16_bf16 v[32:47], v[124:127], v[48:51], v[32:47]
	v_mfma_f32_32x32x16_bf16 v[16:31], v[120:123], v[48:51], v[16:31]
	v_cvt_pk_bf16_f32 v48, v56, v57
	v_cvt_pk_bf16_f32 v49, v58, v59
	v_cvt_pk_bf16_f32 v50, v60, v61
	v_cvt_pk_bf16_f32 v51, v62, v63
	s_nop 1
	v_mfma_f32_32x32x16_bf16 v[32:47], v[108:111], v[48:51], v[32:47]
	v_mfma_f32_32x32x16_bf16 v[16:31], v[104:107], v[48:51], v[16:31]
	s_setprio 0
